# MLA norm1: the four loads of the next row issued at the top of each row iteration (register prefetch), no per-load vmcnt(0)
# speedup vs baseline: 1.0074x; 1.0020x over previous
.LBB0_1276:
	s_or_b64 exec, exec, s[0:1]
	v_lshrrev_b32_e32 v17, 6, v17
	v_readlane_b32 s0, v252, 57
	s_nop 1
	v_add_u32_e32 v22, s0, v17
	s_mov_b32 s0, 0x8400
	v_cmp_gt_i32_e32 vcc, s0, v22
	s_and_saveexec_b64 s[2:3], vcc
	s_cbranch_execz .LBB0_1283
	v_and_b32_e32 v16, 15, v16
	v_cvt_f32_ubyte0_e32 v16, v16
	v_mul_f32_e32 v19, 0xbf549a78, v16
	s_mov_b32 s0, 0xc2fc0000
	v_mov_b32_e32 v20, 0x42800000
	v_cmp_gt_f32_e32 vcc, s0, v19
	v_ashrrev_i32_e32 v23, 31, v22
	v_mov_b32_e32 v25, 0
	v_cndmask_b32_e32 v19, 0, v20, vcc
	v_fmac_f32_e32 v19, 0xbf549a78, v16
	v_exp_f32_e32 v16, v19
	v_not_b32_e32 v19, 63
	v_cndmask_b32_e32 v19, 0, v19, vcc
	v_readlane_b32 s12, v252, 12
	v_ldexp_f32 v43, v16, v19
	v_mbcnt_hi_u32_b32 v16, -1, v1
	v_and_b32_e32 v19, 64, v16
	v_add_u32_e32 v19, 64, v19
	v_xor_b32_e32 v20, 1, v16
	v_cmp_lt_i32_e32 vcc, v20, v19
	v_lshlrev_b32_e32 v24, 1, v14
	v_readlane_b32 s18, v252, 18
	v_cndmask_b32_e32 v20, v16, v20, vcc
	v_lshlrev_b32_e32 v44, 2, v20
	v_xor_b32_e32 v20, 2, v16
	v_cmp_lt_i32_e32 vcc, v20, v19
	v_readlane_b32 s13, v252, 13
	v_readlane_b32 s19, v252, 19
	v_cndmask_b32_e32 v20, v16, v20, vcc
	v_lshlrev_b32_e32 v45, 2, v20
	v_xor_b32_e32 v20, 4, v16
	v_cmp_lt_i32_e32 vcc, v20, v19
	s_add_u32 s12, s18, 0xa800000
	v_readlane_b32 s72, v252, 36
	v_cndmask_b32_e32 v20, v16, v20, vcc
	v_lshlrev_b32_e32 v46, 2, v20
	v_xor_b32_e32 v20, 8, v16
	v_cmp_lt_i32_e32 vcc, v20, v19
	v_readlane_b32 s14, v252, 14
	s_addc_u32 s13, s19, 0
	v_cndmask_b32_e32 v20, v16, v20, vcc
	v_lshlrev_b32_e32 v47, 2, v20
	v_xor_b32_e32 v20, 16, v16
	v_cmp_lt_i32_e32 vcc, v20, v19
	v_readlane_b32 s86, v252, 50
	v_readlane_b32 s87, v252, 51
	v_cndmask_b32_e32 v20, v16, v20, vcc
	v_lshlrev_b32_e32 v48, 2, v20
	v_xor_b32_e32 v20, 32, v16
	v_cmp_lt_i32_e32 vcc, v20, v19
	v_readlane_b32 s15, v252, 15
	s_add_u32 s14, s18, 0x8400000
	v_cndmask_b32_e32 v16, v16, v20, vcc
	v_lshlrev_b32_e32 v49, 2, v16
	v_mov_b32_e32 v16, 0x2000
	v_and_or_b32 v50, v17, 7, v16
	v_lshlrev_b64 v[16:17], 6, v[22:23]
	v_lshl_add_u64 v[16:17], v[16:17], 0, v[24:25]
	v_lshl_add_u64 v[26:27], s[36:37], 0, v[16:17]
	v_lshlrev_b64 v[16:17], 9, v[22:23]
	v_lshlrev_b32_e32 v24, 3, v14
	v_or_b32_e32 v16, v16, v24
	v_readlane_b32 s82, v252, 46
	v_readlane_b32 s83, v252, 47
	v_readlane_b32 s84, v252, 48
	v_readlane_b32 s85, v252, 49
	v_lshl_add_u64 v[28:29], s[86:87], 0, v[16:17]
	v_lshlrev_b64 v[16:17], 12, v[22:23]
	v_readlane_b32 s16, v252, 16
	v_readlane_b32 s17, v252, 17
	s_addc_u32 s15, s19, 0
	s_ashr_i32 s61, s60, 31
	v_lshl_add_u64 v[30:31], s[82:83], 0, v[16:17]
	v_lshl_add_u64 v[16:17], s[84:85], 0, v[24:25]
	s_mov_b64 s[0:1], 0x200
	v_cmp_gt_u32_e64 s[8:9], 16, v14
	s_lshl_b64 s[16:17], s[60:61], 6
	s_lshl_b64 s[18:19], s[60:61], 9
	v_or_b32_e32 v20, 0xc00, v15
	s_lshl_b64 s[20:21], s[60:61], 12
	v_lshl_add_u64 v[32:33], v[16:17], 0, s[0:1]
	v_lshlrev_b64 v[34:35], 10, v[22:23]
	s_lshl_b64 s[22:23], s[60:61], 10
	v_mov_b32_e32 v19, v25
	s_mov_b64 s[24:25], 0
	v_mov_b32_e32 v51, 0x358637bd
	s_mov_b32 s4, 0xf800000
	v_mov_b32_e32 v52, 0x260
	v_lshlrev_b32_e32 v36, 2, v14
	v_lshlrev_b32_e32 v38, 2, v15
	v_mov_b32_e32 v39, v25
	v_mov_b32_e32 v53, 0xa900000
	v_mov_b32_e32 v54, 0xa400000
	v_readlane_b32 s73, v252, 37
	v_readlane_b32 s74, v252, 38
	v_readlane_b32 s75, v252, 39
	v_readlane_b32 s76, v252, 40
	v_readlane_b32 s77, v252, 41
	v_readlane_b32 s78, v252, 42
	v_readlane_b32 s79, v252, 43
	v_readlane_b32 s80, v252, 44
	v_readlane_b32 s81, v252, 45
	v_lshl_add_u64 v[84:85], v[30:31], 0, v[18:19]
	global_load_dwordx4 v[64:67], v[84:85], off
	global_load_dwordx4 v[68:71], v[84:85], off offset:1024
	global_load_dwordx4 v[72:75], v[84:85], off offset:2048
	v_mov_b32_e32 v76, v25
	s_and_saveexec_b64 s[10:11], s[6:7]
	v_lshl_add_u64 v[84:85], v[30:31], 0, v[20:21]
	global_load_dword v76, v[84:85], off
	s_or_b64 exec, exec, s[10:11]
	s_waitcnt vmcnt(0)
	s_branch .LBB0_1279

.LBB0_1279:
	s_waitcnt vmcnt(6)
	v_mov_b32_e32 v56, v64
	v_mov_b32_e32 v57, v65
	v_mov_b32_e32 v58, v66
	v_mov_b32_e32 v59, v67
	v_mov_b32_e32 v86, v68
	v_mov_b32_e32 v87, v69
	v_mov_b32_e32 v88, v70
	v_mov_b32_e32 v89, v71
	v_mov_b32_e32 v77, v72
	v_mov_b32_e32 v78, v73
	v_mov_b32_e32 v79, v74
	v_mov_b32_e32 v80, v75
	v_mov_b32_e32 v81, v76
	v_lshl_add_u64 v[82:83], v[30:31], 0, s[20:21]
	v_lshl_add_u64 v[84:85], v[82:83], 0, v[18:19]
	global_load_dwordx4 v[64:67], v[84:85], off
	global_load_dwordx4 v[68:71], v[84:85], off offset:1024
	global_load_dwordx4 v[72:75], v[84:85], off offset:2048
	v_mov_b32_e32 v76, v25
	s_and_saveexec_b64 s[10:11], s[6:7]
	v_lshl_add_u64 v[84:85], v[82:83], 0, v[20:21]
	global_load_dword v76, v[84:85], off
	s_or_b64 exec, exec, s[10:11]
	v_mul_f32_e32 v14, v57, v57
	s_waitcnt lgkmcnt(0)
	v_mul_f32_e32 v15, v59, v59
	v_fmac_f32_e32 v14, v56, v56
	v_fmac_f32_e32 v15, v58, v58
	v_add_f32_e32 v24, v14, v15
	v_mov_b32_e32 v14, v86
	v_mov_b32_e32 v15, v87
	v_mov_b32_e32 v16, v88
	v_mov_b32_e32 v17, v89
	v_mul_f32_e32 v37, v15, v15
	v_mul_f32_e32 v55, v17, v17
	v_fmac_f32_e32 v37, v14, v14
	v_fmac_f32_e32 v55, v16, v16
	v_add_f32_e32 v37, v37, v55
	v_add_f32_e32 v24, v24, v37
	ds_bpermute_b32 v37, v44, v24
	s_waitcnt lgkmcnt(0)
	v_add_f32_e32 v24, v24, v37
	ds_bpermute_b32 v37, v45, v24
	s_waitcnt lgkmcnt(0)
	v_add_f32_e32 v24, v24, v37
	ds_bpermute_b32 v37, v46, v24
	s_waitcnt lgkmcnt(0)
	v_add_f32_e32 v24, v24, v37
	ds_bpermute_b32 v37, v47, v24
	s_waitcnt lgkmcnt(0)
	v_add_f32_e32 v24, v24, v37
	ds_bpermute_b32 v37, v48, v24
	s_waitcnt lgkmcnt(0)
	v_add_f32_e32 v24, v24, v37
	ds_bpermute_b32 v37, v49, v24
	s_waitcnt lgkmcnt(0)
	v_add_f32_e32 v24, v24, v37
	v_fmamk_f32 v24, v24, 0x3b000000, v51
	v_cmp_gt_f32_e32 vcc, s4, v24
	v_mul_f32_e32 v37, 0x4f800000, v24
	s_nop 0
	v_cndmask_b32_e32 v24, v24, v37, vcc
	v_sqrt_f32_e32 v37, v24
	s_nop 0
	v_add_u32_e32 v55, -1, v37
	v_fma_f32 v60, -v55, v37, v24
	v_cmp_ge_f32_e64 s[0:1], 0, v60
	v_add_u32_e32 v60, 1, v37
	s_nop 0
	v_cndmask_b32_e64 v55, v37, v55, s[0:1]
	v_fma_f32 v37, -v60, v37, v24
	v_cmp_lt_f32_e64 s[0:1], 0, v37
	s_nop 1
	v_cndmask_b32_e64 v37, v55, v60, s[0:1]
	v_mul_f32_e32 v55, 0x37800000, v37
	v_cndmask_b32_e32 v37, v37, v55, vcc
	v_cmp_class_f32_e32 vcc, v24, v52
	s_nop 1
	v_cndmask_b32_e32 v24, v37, v24, vcc
	v_div_scale_f32 v37, s[0:1], v24, v24, 1.0
	v_rcp_f32_e32 v55, v37
	s_nop 0
	v_fma_f32 v60, -v37, v55, 1.0
	v_fmac_f32_e32 v55, v60, v55
	v_div_scale_f32 v60, vcc, 1.0, v24, 1.0
	v_mul_f32_e32 v61, v60, v55
	v_fma_f32 v62, -v37, v61, v60
	v_fmac_f32_e32 v61, v62, v55
	v_fma_f32 v37, -v37, v61, v60
	v_div_fmas_f32 v37, v37, v55, v61
	v_div_fixup_f32 v24, v37, v24, 1.0
	v_mul_f32_e32 v37, v56, v24
	v_mul_f32_e32 v55, v57, v24
	v_mul_f32_e32 v37, v6, v37
	v_mul_f32_e32 v55, v7, v55
	v_mul_f32_e32 v14, v14, v24
	v_mul_f32_e32 v15, v15, v24
	v_cvt_pk_bf16_f32 v56, v37, v55
	v_mul_f32_e32 v37, v58, v24
	v_mul_f32_e32 v55, v59, v24
	v_lshl_add_u64 v[58:59], v[32:33], 0, v[34:35]
	v_mul_f32_e32 v14, v2, v14
	v_mul_f32_e32 v15, v3, v15
	v_mul_f32_e32 v37, v8, v37
	v_mul_f32_e32 v55, v9, v55
	v_cvt_pk_bf16_f32 v57, v37, v55
	global_store_dwordx2 v[58:59], v[56:57], off offset:-512
	v_cvt_pk_bf16_f32 v14, v14, v15
	v_mul_f32_e32 v15, v16, v24
	v_mul_f32_e32 v15, v4, v15
	v_mul_f32_e32 v16, v17, v24
	v_mul_f32_e32 v16, v5, v16
	v_cvt_pk_bf16_f32 v15, v15, v16
	global_store_dwordx2 v[58:59], v[14:15], off
	v_mov_b32_e32 v14, v77
	v_mov_b32_e32 v15, v78
	v_mov_b32_e32 v16, v79
	v_mov_b32_e32 v17, v80
	v_pk_mul_f32 v[40:41], v[16:17], v[16:17]
	v_pk_mul_f32 v[56:57], v[14:15], v[14:15]
	s_nop 0
	v_pk_mov_b32 v[58:59], v[56:57], v[40:41] op_sel:[1,0]
	v_mov_b32_e32 v57, v41
	v_pk_add_f32 v[40:41], v[58:59], v[56:57]
	s_nop 0
	v_add_f32_e32 v24, v40, v41
	ds_bpermute_b32 v37, v44, v24
	s_waitcnt lgkmcnt(0)
	v_add_f32_e32 v24, v24, v37
	ds_bpermute_b32 v37, v45, v24
	s_waitcnt lgkmcnt(0)
	v_add_f32_e32 v24, v24, v37
	ds_bpermute_b32 v37, v46, v24
	s_waitcnt lgkmcnt(0)
	v_add_f32_e32 v24, v24, v37
	ds_bpermute_b32 v37, v47, v24
	s_waitcnt lgkmcnt(0)
	v_add_f32_e32 v24, v24, v37
	ds_bpermute_b32 v37, v48, v24
	s_waitcnt lgkmcnt(0)
	v_add_f32_e32 v24, v24, v37
	ds_bpermute_b32 v37, v49, v24
	s_waitcnt lgkmcnt(0)
	v_add_f32_e32 v24, v24, v37
	v_fmamk_f32 v24, v24, 0x3b800000, v51
	v_cmp_gt_f32_e32 vcc, s4, v24
	v_mul_f32_e32 v37, 0x4f800000, v24
	s_nop 0
	v_cndmask_b32_e32 v24, v24, v37, vcc
	v_sqrt_f32_e32 v37, v24
	s_nop 0
	v_add_u32_e32 v40, -1, v37
	v_fma_f32 v41, -v40, v37, v24
	v_cmp_ge_f32_e64 s[0:1], 0, v41
	v_add_u32_e32 v41, 1, v37
	s_nop 0
	v_cndmask_b32_e64 v40, v37, v40, s[0:1]
	v_fma_f32 v37, -v41, v37, v24
	v_cmp_lt_f32_e64 s[0:1], 0, v37
	s_nop 1
	v_cndmask_b32_e64 v37, v40, v41, s[0:1]
	v_mul_f32_e32 v40, 0x37800000, v37
	v_cndmask_b32_e32 v37, v37, v40, vcc
	v_cmp_class_f32_e32 vcc, v24, v52
	s_nop 1
	v_cndmask_b32_e32 v24, v37, v24, vcc
	v_div_scale_f32 v37, s[0:1], v24, v24, 1.0
	v_rcp_f32_e32 v40, v37
	s_mov_b32 s0, 0x8000
	v_cmp_gt_i32_e64 s[0:1], s0, v22
	v_fma_f32 v41, -v37, v40, 1.0
	v_fmac_f32_e32 v40, v41, v40
	v_div_scale_f32 v41, vcc, 1.0, v24, 1.0
	v_mul_f32_e32 v55, v41, v40
	v_fma_f32 v56, -v37, v55, v41
	v_fmac_f32_e32 v55, v56, v40
	v_fma_f32 v37, -v37, v55, v41
	v_div_fmas_f32 v37, v37, v40, v55
	v_div_fixup_f32 v24, v37, v24, 1.0
	v_pk_mul_f32 v[14:15], v[14:15], v[24:25] op_sel_hi:[1,0]
	v_pk_mul_f32 v[16:17], v[16:17], v[24:25] op_sel_hi:[1,0]
	v_add_u32_e32 v24, 0xffff8000, v22
	v_lshlrev_b64 v[56:57], 10, v[24:25]
	v_lshl_add_u64 v[40:41], s[14:15], 0, v[34:35]
	v_lshl_add_u64 v[56:57], s[12:13], 0, v[56:57]
	v_cndmask_b32_e64 v41, v57, v41, s[0:1]
	v_cndmask_b32_e64 v40, v56, v40, s[0:1]
	v_pk_mul_f32 v[14:15], v[10:11], v[14:15]
	v_pk_mul_f32 v[16:17], v[12:13], v[16:17]
	v_lshl_add_u64 v[40:41], v[40:41], 0, v[38:39]
	global_store_dwordx4 v[40:41], v[14:17], off
	s_nop 1
	v_cvt_pk_bf16_f32 v14, v14, v15
	v_cvt_pk_bf16_f32 v15, v16, v17
	global_store_dwordx2 v[28:29], v[14:15], off
	v_mov_b32_e32 v14, v81
	v_mul_f32_e32 v15, v14, v14
	ds_bpermute_b32 v15, v44, v15
	s_waitcnt lgkmcnt(0)
	v_fmac_f32_e32 v15, v14, v14
	ds_bpermute_b32 v16, v45, v15
	s_waitcnt lgkmcnt(0)
	v_add_f32_e32 v15, v15, v16
	ds_bpermute_b32 v16, v46, v15
	s_waitcnt lgkmcnt(0)
	v_add_f32_e32 v15, v15, v16
	ds_bpermute_b32 v16, v47, v15
	s_waitcnt lgkmcnt(0)
	v_add_f32_e32 v15, v15, v16
	ds_bpermute_b32 v16, v48, v15
	s_waitcnt lgkmcnt(0)
	v_add_f32_e32 v15, v15, v16
	ds_bpermute_b32 v16, v49, v15
	s_waitcnt lgkmcnt(0)
	v_add_f32_e32 v15, v15, v16
	v_fmamk_f32 v15, v15, 0x3d000000, v51
	v_mul_f32_e32 v16, 0x4f800000, v15
	v_cmp_gt_f32_e32 vcc, s4, v15
	s_nop 1
	v_cndmask_b32_e32 v15, v15, v16, vcc
	v_sqrt_f32_e32 v16, v15
	s_nop 0
	v_add_u32_e32 v17, -1, v16
	v_add_u32_e32 v37, 1, v16
	v_fma_f32 v40, -v17, v16, v15
	v_fma_f32 v41, -v37, v16, v15
	v_cmp_ge_f32_e64 s[10:11], 0, v40
	s_nop 1
	v_cndmask_b32_e64 v16, v16, v17, s[10:11]
	v_cmp_lt_f32_e64 s[10:11], 0, v41
	s_nop 1
	v_cndmask_b32_e64 v16, v16, v37, s[10:11]
	v_mul_f32_e32 v17, 0x37800000, v16
	v_cndmask_b32_e32 v16, v16, v17, vcc
	v_cmp_class_f32_e32 vcc, v15, v52
	s_nop 1
	v_cndmask_b32_e32 v15, v16, v15, vcc
	v_div_scale_f32 v16, s[10:11], v15, v15, 1.0
	v_rcp_f32_e32 v17, v16
	v_div_scale_f32 v37, vcc, 1.0, v15, 1.0
	v_fma_f32 v40, -v16, v17, 1.0
	v_fmac_f32_e32 v17, v40, v17
	v_mul_f32_e32 v40, v37, v17
	v_fma_f32 v41, -v16, v40, v37
	v_fmac_f32_e32 v40, v41, v17
	v_fma_f32 v16, -v16, v40, v37
	v_div_fmas_f32 v16, v16, v17, v40
	v_div_fixup_f32 v15, v16, v15, 1.0
	v_mul_f32_e32 v14, v14, v15
	v_mul_f32_e32 v14, v42, v14
	ds_bpermute_b32 v15, v48, v14
	s_and_saveexec_b64 s[10:11], s[6:7]
	s_cbranch_execz .LBB0_1278
	v_ashrrev_i32_e32 v16, 31, v22
	v_lshrrev_b32_e32 v16, 21, v16
	v_add_u32_e32 v16, v22, v16
	v_and_b32_e32 v16, 0xfffff800, v16
	v_sub_u32_e32 v16, v22, v16
	v_cndmask_b32_e64 v16, v50, v16, s[0:1]
	v_cvt_f32_i32_e32 v16, v16
	v_readlane_b32 s72, v252, 12
	v_readlane_b32 s78, v252, 18
	v_readlane_b32 s79, v252, 19
	v_mul_f32_e32 v16, v43, v16
	v_mul_f32_e32 v17, 0.15915494, v16
	v_rndne_f32_e32 v17, v17
	v_fmac_f32_e32 v16, 0xc0c90000, v17
	v_fmac_f32_e32 v16, 0xbafdaa22, v17
	v_mul_f32_e32 v16, 0.15915494, v16
	v_cos_f32_e32 v17, v16
	v_sin_f32_e32 v16, v16
	v_mov_b32_e32 v37, v25
	v_readlane_b32 s73, v252, 13
	v_readlane_b32 s74, v252, 14
	s_waitcnt lgkmcnt(0)
	v_mul_f32_e32 v15, v16, v15
	v_cndmask_b32_e64 v40, v15, -v15, s[8:9]
	v_fmac_f32_e32 v40, v17, v14
	v_cndmask_b32_e64 v15, 0, v23, s[0:1]
	v_cndmask_b32_e64 v14, v24, v22, s[0:1]
	v_cndmask_b32_e64 v24, v53, v54, s[0:1]
	v_lshl_add_u64 v[16:17], s[78:79], 0, v[24:25]
	v_lshlrev_b64 v[14:15], 7, v[14:15]
	v_lshl_add_u64 v[14:15], v[16:17], 0, v[14:15]
	v_lshl_add_u64 v[14:15], v[14:15], 0, v[36:37]
	v_readlane_b32 s75, v252, 15
	v_readlane_b32 s76, v252, 16
	v_readlane_b32 s77, v252, 17
	global_store_dword v[14:15], v40, off
	v_cvt_pk_bf16_f32 v14, v40, v25
	global_store_short v[26:27], v14, off
	s_branch .LBB0_1278
